# grid barrier: single-level arrival counter (last arriver stores the release flag directly), one fewer serialized atomic hop
# baseline (speedup 1.0000x reference)
.LBB0_860:
	s_mov_b64 s[4:5], exec
	v_mbcnt_lo_u32_b32 v1, s4, 0
	v_mbcnt_hi_u32_b32 v1, s5, v1
	v_cmp_eq_u32_e32 vcc, 0, v1
	buffer_wbl2 sc1
	s_waitcnt vmcnt(0)
	s_and_saveexec_b64 s[6:7], vcc
	s_cbranch_execz .LBB0_862
	s_bcnt1_i32_b64 s4, s[4:5]
	v_mov_b32_e32 v2, s4
	v_readlane_b32 s4, v253, 21
	v_readlane_b32 s5, v253, 22
	s_nop 4
	global_atomic_add v2, v131, v2, s[4:5] sc0
.LBB0_862:
	s_or_b64 exec, exec, s[6:7]
	v_readlane_b32 s4, v253, 14
	v_readlane_b32 s5, v253, 15
	s_load_dword s4, s[4:5], 0x0
	v_readlane_b32 s5, v253, 16
	s_waitcnt lgkmcnt(0)
	s_nop 0
	s_waitcnt vmcnt(0)
	v_readfirstlane_b32 s5, v2
	s_nop 0
	s_nop 0
	v_add_u32_e32 v1, s5, v1
	v_readlane_b32 s5, v254, 19
	s_mul_i32 s4, s4, s5
	s_add_i32 s4, s4, -1
	v_cmp_eq_u32_e32 vcc, s4, v1
	s_and_saveexec_b64 s[4:5], vcc
	s_cbranch_execz .LBB0_867
	s_branch .Lflat_866
	s_mov_b64 s[8:9], exec
	v_mbcnt_lo_u32_b32 v1, s8, 0
	v_mbcnt_hi_u32_b32 v1, s9, v1
	v_cmp_eq_u32_e32 vcc, 0, v1
	s_and_saveexec_b64 s[6:7], vcc
	s_cbranch_execz .LBB0_865
	s_bcnt1_i32_b64 s8, s[8:9]
	v_mov_b32_e32 v2, s8
	v_readlane_b32 s8, v253, 21
	v_readlane_b32 s9, v253, 22
	s_nop 4
	global_atomic_add v2, v131, v2, s[8:9] sc0

.Lflat_866:
	v_readlane_b32 s6, v254, 19
	s_nop 1
	v_mov_b32_e32 v1, s6
	v_readlane_b32 s6, v253, 17
	v_readlane_b32 s7, v253, 18
	s_nop 4
	global_store_dword v131, v1, s[6:7] sc1
